# MLA and dilated phases deduplicated across layers; V-fragment LDS reads hoisted above staging in MLA loop; dilated-attention next-unit K/V/Q prefetch into spare VGPRs
# speedup vs baseline: 1.0065x; 1.0065x over previous
.LBB0_174:
	s_or_b64 exec, exec, s[52:53]
	s_mov_b32 s100, 0
.Ldil_body:
	s_cmpk_gt_i32 s12, 0x13ff
	s_cbranch_scc1 .LBB0_211
	s_add_u32 s88, s70, 0x77a0000
	s_addc_u32 s89, s71, 0
	v_and_b32_e32 v0, 0x3fffffc0, v16
	s_add_i32 s0, 0, 0x18000
	v_ashrrev_i32_e32 v113, 3, v16
	v_lshl_add_u32 v1, v0, 2, s0
	v_lshlrev_b32_e32 v0, 1, v14
	v_and_b32_e32 v3, 32, v0
	v_lshlrev_b32_e32 v0, 4, v14
	v_lshlrev_b32_e32 v5, 3, v16
	v_lshrrev_b32_e32 v2, 1, v113
	v_and_b32_e32 v8, 3, v113
	v_and_b32_e32 v4, 0xc0, v0
	v_and_b32_e32 v0, 56, v5
	v_and_or_b32 v2, v2, 4, v8
	v_lshlrev_b32_e32 v6, 1, v0
	v_lshlrev_b32_e32 v8, 6, v2
	v_lshlrev_b32_e32 v2, 1, v113
	v_and_b32_e32 v9, 0x1fffff0, v113
	s_movk_i32 s0, 0x70
	v_and_or_b32 v2, v2, 8, v9
	v_bitop3_b32 v10, v6, v16, s0 bitop3:0x78
	s_add_i32 s0, 0, 0x18800
	v_lshrrev_b32_e32 v2, 2, v2
	v_bfe_u32 v9, v5, 5, 1
	v_lshl_add_u32 v11, v18, 12, s0
	s_movk_i32 s0, 0x118
	v_or_b32_e32 v9, v2, v9
	v_and_or_b32 v3, v17, s0, v3
	s_add_i32 s0, 0, 0xc000
	v_and_b32_e32 v7, 48, v6
	v_bfe_u32 v12, v14, 5, 1
	v_lshl_add_u32 v9, v9, 9, 0
	s_cmp_lg_u32 s0, -1
	v_and_b32_e32 v112, 31, v14
	v_add3_u32 v115, v9, v8, v7
	v_lshlrev_b32_e32 v7, 2, v12
	v_lshlrev_b32_e32 v8, 4, v12
	s_cselect_b32 s0, s0, 0
	v_cvt_f32_ubyte0_e32 v117, v7
	v_ashrrev_i32_e32 v7, 7, v16
	v_and_b32_e32 v5, 0x70, v5
	v_lshl_add_u32 v9, v112, 7, 0
	v_add3_u32 v3, v4, s0, v3
	v_cmp_gt_u32_e64 s[0:1], 32, v15
	v_or_b32_e32 v15, 32, v8
	v_lshl_add_u32 v4, v112, 1, v11
	v_bfe_u32 v119, v14, 3, 3
	v_add_u32_e32 v6, v11, v6
	v_add_u32_e32 v11, 1, v7
	v_add_u32_e32 v14, 2, v7
	v_xad_u32 v124, v15, v5, v9
	v_or_b32_e32 v15, 64, v8
	s_add_u32 s90, s70, 0x137a0000
	v_lshlrev_b32_e32 v120, 13, v7
	v_lshlrev_b32_e32 v122, 13, v11
	v_lshlrev_b32_e32 v123, 13, v14
	v_xad_u32 v125, v15, v5, v9
	v_or_b32_e32 v15, 0x60, v8
	v_or_b32_e32 v134, 8, v119
	v_or_b32_e32 v135, 16, v119
	v_or_b32_e32 v136, 24, v119
	s_addc_u32 s91, s71, 0
	v_mov_b32_e32 v109, 0
	v_lshlrev_b32_e32 v2, 3, v12
	v_lshl_add_u32 v13, v113, 7, 0
	v_lshl_add_u32 v118, v112, 2, v1
	v_xad_u32 v121, v8, v5, v9
	v_xad_u32 v126, v15, v5, v9
	v_lshlrev_b32_e32 v127, 6, v7
	v_add_u32_e32 v130, v3, v120
	v_add_u32_e32 v131, v3, v122
	v_add_u32_e32 v132, v3, v123
	v_add_u32_e32 v133, v1, v8
	v_lshlrev_b32_e32 v1, 9, v12
	v_lshlrev_b32_e32 v3, 7, v119
	v_lshlrev_b32_e32 v5, 7, v134
	v_lshlrev_b32_e32 v7, 7, v135
	v_lshlrev_b32_e32 v8, 7, v136
	s_add_u32 s92, s70, 0x1eea0000
	s_mov_b32 s10, 0x42000000
	s_mov_b32 s52, 2.0
	s_mov_b32 s54, 0x42080000
	s_mov_b32 s56, 0x41000000
	s_mov_b32 s58, 0x42200000
	s_mov_b32 s60, 0x41200000
	s_mov_b32 s62, 0x42280000
	s_mov_b32 s64, 0x41800000
	s_mov_b32 s66, 0x42400000
	s_mov_b32 s72, 0x41900000
	s_mov_b32 s74, 0x42480000
	s_mov_b32 s76, 0x41c00000
	s_mov_b32 s78, 0x42600000
	s_mov_b32 s80, 0x41d00000
	s_mov_b32 s82, 0x42680000
	s_mov_b32 s24, s84
	s_mov_b32 s9, 0
	v_lshlrev_b32_e32 v114, 5, v18
	v_add_u32_e32 v116, 0xc000, v115
	v_lshlrev_b32_e32 v128, 6, v11
	v_lshlrev_b32_e32 v129, 6, v14
	s_addc_u32 s93, s71, 0
	v_lshlrev_b32_e32 v108, 1, v0
	v_lshlrev_b32_e32 v110, 1, v2
	v_mov_b32_e32 v111, v109
	v_add_u32_e32 v137, v13, v10
	s_mov_b32 s11, 0x42040000
	s_mov_b32 s94, 0x42800000
	s_mov_b32 s95, 0xff61b1e6
	s_mov_b32 s53, 0x40400000
	s_mov_b32 s55, 0x420c0000
	s_mov_b32 s57, 0x41100000
	s_mov_b32 s59, 0x42240000
	s_mov_b32 s61, 0x41300000
	s_mov_b32 s63, 0x422c0000
	s_mov_b32 s65, 0x41880000
	s_mov_b32 s67, 0x42440000
	s_mov_b32 s73, 0x41980000
	s_mov_b32 s75, 0x424c0000
	s_mov_b32 s77, 0x41c80000
	s_mov_b32 s79, 0x42640000
	s_mov_b32 s81, 0x41d80000
	s_mov_b32 s83, 0x426c0000
	v_add_u32_e32 v138, v4, v1
	v_add_u32_e32 v139, v6, v3
	v_add_u32_e32 v140, v6, v5
	v_add_u32_e32 v141, v6, v7
	v_add_u32_e32 v142, v6, v8
	v_mov_b32_e32 v143, 0xf149f2ca
	s_mov_b32 s96, s12
	s_mov_b32 s25, s12
	s_cmpk_ge_u32 s25, 0x1400
	s_cbranch_scc1 .Ldil_pf_skip_a
	s_mul_hi_u32 s26, s25, 0x2aaaaab
	s_mul_i32 s27, s26, 0x60
	s_sub_u32 s27, s25, s27
	s_lshr_b32 s28, s27, 5
	s_and_b32 s27, s27, 31
	s_sub_u32 s29, s25, 0xc00
	s_lshr_b32 s30, s29, 5
	s_and_b32 s29, s29, 31
	s_lshr_b32 s31, s29, 3
	s_min_u32 s31, s31, 2
	s_lshl_b32 s32, s31, 3
	s_sub_u32 s29, s29, s32
	s_movk_i32 s101, 0x800
	s_cmpk_lt_u32 s25, 0xc00
	s_cselect_b32 s26, s26, s30
	s_cselect_b32 s28, s28, s31
	s_cselect_b32 s27, s27, s29
	s_cselect_b32 s98, 0x2000, s101
	s_cselect_b32 s30, 13, 11
	s_cselect_b32 s31, 0, 0x8000
	s_lshr_b32 s29, s26, 3
	s_lshl_b32 s29, s29, s30
	s_add_u32 s29, s29, s31
	s_and_b32 s26, s26, 7
	s_lshl_b32 s28, s28, 1
	s_lshr_b32 s30, s27, s28
	s_lshl_b32 s31, s30, s28
	s_sub_u32 s27, s27, s31
	s_add_u32 s29, s29, s27
	s_lshl_b32 s30, s30, 8
	s_lshr_b32 s98, s98, s28
	s_sub_u32 s98, s98, 1
	s_mul_i32 s26, s26, 0x600000
	s_sub_u32 s31, s30, 64
	v_add_u32_e32 v178, s31, v113
	v_add_u32_e32 v179, s26, v108
	v_add_u32_e32 v245, 0x3000000, v179
	v_med3_i32 v246, v178, 0, s98
	v_lshlrev_b32_e32 v246, s28, v246
	v_add_u32_e32 v246, s29, v246
	v_lshl_add_u32 v246, v246, 7, v245
	global_load_dwordx4 v[180:183], v246, s[88:89]
	v_add_u32_e32 v247, 0x3000000, v246
	global_load_dwordx4 v[184:187], v247, s[88:89]
	v_add_u32_e32 v246, 64, v178
	v_med3_i32 v246, v246, 0, s98
	v_lshlrev_b32_e32 v246, s28, v246
	v_add_u32_e32 v246, s29, v246
	v_lshl_add_u32 v246, v246, 7, v245
	global_load_dwordx4 v[188:191], v246, s[88:89]
	v_add_u32_e32 v247, 0x3000000, v246
	global_load_dwordx4 v[192:195], v247, s[88:89]
	v_add_u32_e32 v246, 128, v178
	v_med3_i32 v246, v246, 0, s98
	v_lshlrev_b32_e32 v246, s28, v246
	v_add_u32_e32 v246, s29, v246
	v_lshl_add_u32 v246, v246, 7, v245
	global_load_dwordx4 v[196:199], v246, s[88:89]
	v_add_u32_e32 v247, 0x3000000, v246
	global_load_dwordx4 v[200:203], v247, s[88:89]
	v_add_u32_e32 v246, 192, v178
	v_med3_i32 v246, v246, 0, s98
	v_lshlrev_b32_e32 v246, s28, v246
	v_add_u32_e32 v246, s29, v246
	v_lshl_add_u32 v246, v246, 7, v245
	global_load_dwordx4 v[204:207], v246, s[88:89]
	v_add_u32_e32 v247, 0x3000000, v246
	global_load_dwordx4 v[208:211], v247, s[88:89]
	v_add_u32_e32 v246, 256, v178
	v_med3_i32 v246, v246, 0, s98
	v_lshlrev_b32_e32 v246, s28, v246
	v_add_u32_e32 v246, s29, v246
	v_lshl_add_u32 v246, v246, 7, v245
	global_load_dwordx4 v[212:215], v246, s[88:89]
	v_add_u32_e32 v247, 0x3000000, v246
	global_load_dwordx4 v[216:219], v247, s[88:89]
	v_add_u32_e32 v246, 320, v178
	v_med3_i32 v246, v246, 0, s98
	v_lshlrev_b32_e32 v246, s28, v246
	v_add_u32_e32 v246, s29, v246
	v_lshl_add_u32 v246, v246, 7, v245
	global_load_dwordx4 v[220:223], v246, s[88:89]
	v_add_u32_e32 v247, 0x3000000, v246
	global_load_dwordx4 v[224:227], v247, s[88:89]
	v_add_u32_e32 v246, s30, v114
	v_or_b32_e32 v246, v246, v112
	v_min_i32_e32 v246, s98, v246
	v_lshlrev_b32_e32 v246, s28, v246
	v_add_u32_e32 v246, s29, v246
	v_add_u32_e32 v247, s26, v110
	v_lshl_add_u32 v246, v246, 7, v247
	global_load_dwordx4 v[228:231], v246, s[88:89]
	global_load_dwordx4 v[232:235], v246, s[88:89] offset:32
	global_load_dwordx4 v[236:239], v246, s[88:89] offset:64
	global_load_dwordx4 v[240:243], v246, s[88:89] offset:96
.Ldil_pf_skip_a:
	s_branch .LBB0_178

.LBB0_195:
	s_lshl_b32 s4, s8, 11
	s_add_i32 s4, s4, 0x8000
	s_lshl_b32 s5, s8, 13
	s_and_b64 s[2:3], s[2:3], exec
	s_cselect_b32 s33, s5, s4
	s_lshl_b32 s20, s19, 8
	s_and_b32 s17, s7, 7
	s_cmp_eq_u32 s16, 1
	s_cselect_b64 s[2:3], -1, 0
	s_and_b64 s[4:5], s[2:3], exec
	s_cselect_b32 s7, 2, 4
	s_cmp_eq_u32 s16, 0
	s_cselect_b64 s[4:5], -1, 0
	s_and_b64 s[22:23], s[4:5], exec
	s_cselect_b32 s97, 0, s7
	s_lshr_b32 s8, s18, s97
	s_sub_i32 s18, s20, 64
	s_waitcnt lgkmcnt(0)
	v_add_u32_e32 v44, s18, v113
	s_add_i32 s21, s8, -1
	v_min_i32_e32 v0, s21, v44
	v_cmp_lt_i32_e32 vcc, -1, v44
	v_add_u32_e32 v8, s20, v113
	v_min_i32_e32 v9, s21, v8
	v_cndmask_b32_e32 v0, 0, v0, vcc
	v_cmp_lt_i32_e32 vcc, -1, v8
	s_waitcnt vmcnt(3)
	v_add_u32_e32 v16, 0x80, v44
	s_movk_i32 s22, 0xff7f
	s_add_i32 s33, s33, s6
	s_mul_i32 s6, s17, 0x600000
	v_cndmask_b32_e32 v8, 0, v9, vcc
	v_min_i32_e32 v16, s21, v16
	v_cmp_lt_i32_e32 vcc, s22, v44
	s_add_u32 s6, s88, s6
	s_addc_u32 s7, s89, 0
	v_cndmask_b32_e32 v16, 0, v16, vcc
	v_lshlrev_b32_e32 v0, s97, v0
	v_lshlrev_b32_e32 v8, s97, v8
	v_lshlrev_b32_e32 v16, s97, v16
	s_add_u32 s84, s6, 0x3000000
	v_add_u32_e32 v0, s33, v0
	v_add_u32_e32 v8, s33, v8
	v_add_u32_e32 v16, s33, v16
	s_addc_u32 s85, s7, 0
	v_ashrrev_i32_e32 v1, 31, v0
	v_ashrrev_i32_e32 v9, 31, v8
	v_ashrrev_i32_e32 v17, 31, v16
	s_add_u32 s86, s6, 0x6000000
	v_lshlrev_b64 v[0:1], 7, v[0:1]
	v_lshlrev_b64 v[8:9], 7, v[8:9]
	v_lshlrev_b64 v[16:17], 7, v[16:17]
	s_addc_u32 s87, s7, 0
	v_or_b32_e32 v0, v0, v108
	v_or_b32_e32 v8, v8, v108
	v_or_b32_e32 v16, v16, v108
	v_lshl_add_u64 v[2:3], s[84:85], 0, v[0:1]
	v_lshl_add_u64 v[4:5], s[86:87], 0, v[0:1]
	v_lshl_add_u64 v[10:11], s[84:85], 0, v[8:9]
	v_lshl_add_u64 v[12:13], s[86:87], 0, v[8:9]
	v_lshl_add_u64 v[18:19], s[84:85], 0, v[16:17]
	v_lshl_add_u64 v[16:17], s[86:87], 0, v[16:17]
	s_nop 0
	s_nop 0
	s_nop 0
	s_nop 0
	v_add_u32_e32 v16, 0xc0, v44
	s_movk_i32 s22, 0xff3f
	v_min_i32_e32 v16, s21, v16
	v_cmp_lt_i32_e32 vcc, s22, v44
	s_movk_i32 s22, 0xfeff
	v_add_u32_e32 v144, s20, v114
	v_cndmask_b32_e32 v16, 0, v16, vcc
	v_lshlrev_b32_e32 v16, s97, v16
	v_add_u32_e32 v16, s33, v16
	v_ashrrev_i32_e32 v17, 31, v16
	v_lshlrev_b64 v[16:17], 7, v[16:17]
	v_or_b32_e32 v16, v16, v108
	v_lshl_add_u64 v[18:19], s[84:85], 0, v[16:17]
	v_lshl_add_u64 v[16:17], s[86:87], 0, v[16:17]
	v_add_u32_e32 v16, 0x100, v44
	v_min_i32_e32 v16, s21, v16
	v_cmp_lt_i32_e32 vcc, s22, v44
	s_movk_i32 s22, 0xfebf
	v_or_b32_e32 v145, v144, v112
	v_cndmask_b32_e32 v16, 0, v16, vcc
	v_lshlrev_b32_e32 v16, s97, v16
	v_add_u32_e32 v16, s33, v16
	v_ashrrev_i32_e32 v17, 31, v16
	v_lshlrev_b64 v[16:17], 7, v[16:17]
	v_or_b32_e32 v16, v16, v108
	v_lshl_add_u64 v[18:19], s[84:85], 0, v[16:17]
	v_lshl_add_u64 v[16:17], s[86:87], 0, v[16:17]
	v_add_u32_e32 v16, 0x140, v44
	v_min_i32_e32 v16, s21, v16
	v_cmp_lt_i32_e32 vcc, s22, v44
	s_nop 1
	v_cndmask_b32_e32 v16, 0, v16, vcc
	v_lshlrev_b32_e32 v16, s97, v16
	v_add_u32_e32 v16, s33, v16
	v_ashrrev_i32_e32 v17, 31, v16
	v_lshlrev_b64 v[16:17], 7, v[16:17]
	v_or_b32_e32 v16, v16, v108
	v_lshl_add_u64 v[18:19], s[84:85], 0, v[16:17]
	v_lshl_add_u64 v[16:17], s[86:87], 0, v[16:17]
	v_min_i32_e32 v16, s21, v145
	v_lshlrev_b32_e32 v16, s97, v16
	v_add_u32_e32 v16, s33, v16
	v_ashrrev_i32_e32 v17, 31, v16
	v_lshlrev_b64 v[16:17], 7, v[16:17]
	v_lshl_add_u64 v[16:17], s[6:7], 0, v[16:17]
	v_lshl_add_u64 v[52:53], v[16:17], 0, v[110:111]
	v_cmp_gt_i32_e32 vcc, s8, v144
	s_waitcnt vmcnt(0)
	ds_write_b128 v137, v[180:183]
	ds_write_b128 v115, v[184:187] offset:49152
	ds_write_b128 v137, v[188:191] offset:8192
	ds_write_b128 v115, v[192:195] offset:57344
	ds_write_b128 v137, v[196:199] offset:16384
	ds_write_b128 v116, v[200:203] offset:16384
	ds_write_b128 v137, v[204:207] offset:24576
	ds_write_b128 v116, v[208:211] offset:24576
	ds_write_b128 v137, v[212:215] offset:32768
	ds_write_b128 v116, v[216:219] offset:32768
	ds_write_b128 v137, v[220:223] offset:40960
	ds_write_b128 v116, v[224:227] offset:40960
	v_mov_b32_e32 v16, v228
	v_mov_b32_e32 v17, v229
	v_mov_b32_e32 v18, v230
	v_mov_b32_e32 v19, v231
	v_mov_b32_e32 v104, v232
	v_mov_b32_e32 v105, v233
	v_mov_b32_e32 v106, v234
	v_mov_b32_e32 v107, v235
	v_mov_b32_e32 v100, v236
	v_mov_b32_e32 v101, v237
	v_mov_b32_e32 v102, v238
	v_mov_b32_e32 v103, v239
	v_mov_b32_e32 v96, v240
	v_mov_b32_e32 v97, v241
	v_mov_b32_e32 v98, v242
	v_mov_b32_e32 v99, v243
	s_waitcnt lgkmcnt(0)
	s_barrier
	s_add_u32 s25, s96, s13
	s_cmpk_ge_u32 s25, 0x1400
	s_cbranch_scc1 .Ldil_pf_skip_b
	s_mul_hi_u32 s26, s25, 0x2aaaaab
	s_mul_i32 s27, s26, 0x60
	s_sub_u32 s27, s25, s27
	s_lshr_b32 s28, s27, 5
	s_and_b32 s27, s27, 31
	s_sub_u32 s29, s25, 0xc00
	s_lshr_b32 s30, s29, 5
	s_and_b32 s29, s29, 31
	s_lshr_b32 s31, s29, 3
	s_min_u32 s31, s31, 2
	s_lshl_b32 s32, s31, 3
	s_sub_u32 s29, s29, s32
	s_movk_i32 s101, 0x800
	s_cmpk_lt_u32 s25, 0xc00
	s_cselect_b32 s26, s26, s30
	s_cselect_b32 s28, s28, s31
	s_cselect_b32 s27, s27, s29
	s_cselect_b32 s98, 0x2000, s101
	s_cselect_b32 s30, 13, 11
	s_cselect_b32 s31, 0, 0x8000
	s_lshr_b32 s29, s26, 3
	s_lshl_b32 s29, s29, s30
	s_add_u32 s29, s29, s31
	s_and_b32 s26, s26, 7
	s_lshl_b32 s28, s28, 1
	s_lshr_b32 s30, s27, s28
	s_lshl_b32 s31, s30, s28
	s_sub_u32 s27, s27, s31
	s_add_u32 s29, s29, s27
	s_lshl_b32 s30, s30, 8
	s_lshr_b32 s98, s98, s28
	s_sub_u32 s98, s98, 1
	s_mul_i32 s26, s26, 0x600000
	s_sub_u32 s31, s30, 64
	v_add_u32_e32 v178, s31, v113
	v_add_u32_e32 v179, s26, v108
	v_add_u32_e32 v245, 0x3000000, v179
	v_med3_i32 v246, v178, 0, s98
	v_lshlrev_b32_e32 v246, s28, v246
	v_add_u32_e32 v246, s29, v246
	v_lshl_add_u32 v246, v246, 7, v245
	global_load_dwordx4 v[180:183], v246, s[88:89]
	v_add_u32_e32 v247, 0x3000000, v246
	global_load_dwordx4 v[184:187], v247, s[88:89]
	v_add_u32_e32 v246, 64, v178
	v_med3_i32 v246, v246, 0, s98
	v_lshlrev_b32_e32 v246, s28, v246
	v_add_u32_e32 v246, s29, v246
	v_lshl_add_u32 v246, v246, 7, v245
	global_load_dwordx4 v[188:191], v246, s[88:89]
	v_add_u32_e32 v247, 0x3000000, v246
	global_load_dwordx4 v[192:195], v247, s[88:89]
	v_add_u32_e32 v246, 128, v178
	v_med3_i32 v246, v246, 0, s98
	v_lshlrev_b32_e32 v246, s28, v246
	v_add_u32_e32 v246, s29, v246
	v_lshl_add_u32 v246, v246, 7, v245
	global_load_dwordx4 v[196:199], v246, s[88:89]
	v_add_u32_e32 v247, 0x3000000, v246
	global_load_dwordx4 v[200:203], v247, s[88:89]
	v_add_u32_e32 v246, 192, v178
	v_med3_i32 v246, v246, 0, s98
	v_lshlrev_b32_e32 v246, s28, v246
	v_add_u32_e32 v246, s29, v246
	v_lshl_add_u32 v246, v246, 7, v245
	global_load_dwordx4 v[204:207], v246, s[88:89]
	v_add_u32_e32 v247, 0x3000000, v246
	global_load_dwordx4 v[208:211], v247, s[88:89]
	v_add_u32_e32 v246, 256, v178
	v_med3_i32 v246, v246, 0, s98
	v_lshlrev_b32_e32 v246, s28, v246
	v_add_u32_e32 v246, s29, v246
	v_lshl_add_u32 v246, v246, 7, v245
	global_load_dwordx4 v[212:215], v246, s[88:89]
	v_add_u32_e32 v247, 0x3000000, v246
	global_load_dwordx4 v[216:219], v247, s[88:89]
	v_add_u32_e32 v246, 320, v178
	v_med3_i32 v246, v246, 0, s98
	v_lshlrev_b32_e32 v246, s28, v246
	v_add_u32_e32 v246, s29, v246
	v_lshl_add_u32 v246, v246, 7, v245
	global_load_dwordx4 v[220:223], v246, s[88:89]
	v_add_u32_e32 v247, 0x3000000, v246
	global_load_dwordx4 v[224:227], v247, s[88:89]
	v_add_u32_e32 v246, s30, v114
	v_or_b32_e32 v246, v246, v112
	v_min_i32_e32 v246, s98, v246
	v_lshlrev_b32_e32 v246, s28, v246
	v_add_u32_e32 v246, s29, v246
	v_add_u32_e32 v247, s26, v110
	v_lshl_add_u32 v246, v246, 7, v247
	global_load_dwordx4 v[228:231], v246, s[88:89]
	global_load_dwordx4 v[232:235], v246, s[88:89] offset:32
	global_load_dwordx4 v[236:239], v246, s[88:89] offset:64
	global_load_dwordx4 v[240:243], v246, s[88:89] offset:96
.Ldil_pf_skip_b:
	s_and_saveexec_b64 s[84:85], vcc
	s_cbranch_execz .LBB0_177
	s_cmp_eq_u32 s19, 0
	s_cselect_b64 s[6:7], -1, 0
	s_addk_i32 s20, 0x140
	s_cmp_gt_u32 s20, s8
	s_cselect_b64 s[20:21], -1, 0
	s_or_b64 s[6:7], s[6:7], s[20:21]
	s_and_b64 s[2:3], s[2:3], exec
	s_cselect_b32 s19, 4, 16
	s_and_b64 s[2:3], s[4:5], exec
	s_cselect_b32 s2, 1, s19
	s_add_i32 s3, s17, 1
	v_cvt_f32_ubyte0_e32 v0, s3
	v_exp_f32_e64 v0, -v0
	v_cvt_f32_ubyte0_e32 v1, s2
	v_add_u32_e32 v4, v121, v120
	v_add_u32_e32 v150, v124, v120
	v_mul_f32_e32 v154, v0, v1
	ds_read_b128 v[0:3], v4
	ds_read_b128 v[4:7], v4 offset:4096
	s_waitcnt lgkmcnt(0)
	v_mfma_f32_32x32x16_bf16 v[80:95], v[4:7], v[16:19], 0
	v_add_u32_e32 v4, v121, v122
	v_add_u32_e32 v170, s18, v127
	s_mov_b64 s[86:87], -1
	s_and_b64 vcc, exec, s[6:7]
	v_mfma_f32_32x32x16_bf16 v[64:79], v[0:3], v[16:19], 0
	ds_read_b128 v[0:3], v4
	ds_read_b128 v[4:7], v4 offset:4096
	s_waitcnt lgkmcnt(0)
	v_mfma_f32_32x32x16_bf16 v[48:63], v[4:7], v[16:19], 0
	v_add_u32_e32 v4, v121, v123
	v_mfma_f32_32x32x16_bf16 v[32:47], v[0:3], v[16:19], 0
	ds_read_b128 v[0:3], v4
	ds_read_b128 v[20:23], v4 offset:4096
	ds_read_b128 v[146:149], v150
	ds_read_b128 v[150:153], v150 offset:4096
	s_waitcnt lgkmcnt(0)
	v_mfma_f32_32x32x16_bf16 v[80:95], v[150:153], v[104:107], v[80:95]
	v_add_u32_e32 v150, v124, v122
	v_mfma_f32_32x32x16_bf16 v[64:79], v[146:149], v[104:107], v[64:79]
	ds_read_b128 v[146:149], v150
	ds_read_b128 v[150:153], v150 offset:4096
	v_mfma_f32_32x32x16_bf16 v[0:15], v[0:3], v[16:19], 0
	v_mfma_f32_32x32x16_bf16 v[16:31], v[20:23], v[16:19], 0
	s_waitcnt lgkmcnt(0)
	v_mfma_f32_32x32x16_bf16 v[48:63], v[150:153], v[104:107], v[48:63]
	v_add_u32_e32 v150, v124, v123
	v_mfma_f32_32x32x16_bf16 v[32:47], v[146:149], v[104:107], v[32:47]
	ds_read_b128 v[146:149], v150
	ds_read_b128 v[150:153], v150 offset:4096
	s_waitcnt lgkmcnt(1)
	v_mfma_f32_32x32x16_bf16 v[0:15], v[146:149], v[104:107], v[0:15]
	v_add_u32_e32 v146, v125, v120
	s_waitcnt lgkmcnt(0)
	v_mfma_f32_32x32x16_bf16 v[16:31], v[150:153], v[104:107], v[16:31]
	ds_read_b128 v[104:107], v146
	ds_read_b128 v[146:149], v146 offset:4096
	s_waitcnt lgkmcnt(0)
	v_mfma_f32_32x32x16_bf16 v[80:95], v[146:149], v[100:103], v[80:95]
	v_add_u32_e32 v146, v125, v122
	v_mfma_f32_32x32x16_bf16 v[64:79], v[104:107], v[100:103], v[64:79]
	ds_read_b128 v[104:107], v146
	ds_read_b128 v[146:149], v146 offset:4096
	s_waitcnt lgkmcnt(0)
	v_mfma_f32_32x32x16_bf16 v[48:63], v[146:149], v[100:103], v[48:63]
	v_add_u32_e32 v146, v125, v123
	v_mfma_f32_32x32x16_bf16 v[32:47], v[104:107], v[100:103], v[32:47]
	ds_read_b128 v[104:107], v146
	ds_read_b128 v[146:149], v146 offset:4096
	s_waitcnt lgkmcnt(1)
	v_mfma_f32_32x32x16_bf16 v[0:15], v[104:107], v[100:103], v[0:15]
	v_add_u32_e32 v104, v126, v120
	s_waitcnt lgkmcnt(0)
	v_mfma_f32_32x32x16_bf16 v[16:31], v[146:149], v[100:103], v[16:31]
	ds_read_b128 v[100:103], v104
	ds_read_b128 v[104:107], v104 offset:4096
	s_waitcnt lgkmcnt(0)
	v_mfma_f32_32x32x16_bf16 v[80:95], v[104:107], v[96:99], v[80:95]
	v_add_u32_e32 v104, v126, v122
	v_mfma_f32_32x32x16_bf16 v[64:79], v[100:103], v[96:99], v[64:79]
	ds_read_b128 v[100:103], v104
	ds_read_b128 v[104:107], v104 offset:4096
	s_waitcnt lgkmcnt(0)
	v_mfma_f32_32x32x16_bf16 v[48:63], v[104:107], v[96:99], v[48:63]
	v_add_u32_e32 v104, v126, v123
	v_mfma_f32_32x32x16_bf16 v[32:47], v[100:103], v[96:99], v[32:47]
	ds_read_b128 v[100:103], v104
	ds_read_b128 v[104:107], v104 offset:4096
	s_waitcnt lgkmcnt(1)
	v_mfma_f32_32x32x16_bf16 v[0:15], v[100:103], v[96:99], v[0:15]
	s_waitcnt lgkmcnt(0)
	v_mfma_f32_32x32x16_bf16 v[16:31], v[104:107], v[96:99], v[16:31]
	v_sub_u32_e32 v97, v170, v145
	v_cvt_f32_i32_e32 v97, v97
	v_mul_f32_e32 v96, 0xbfb8aa3b, v154
	v_add_f32_e32 v98, v117, v97
	v_add_f32_e32 v171, 1.0, v98
	v_cmp_le_f32_e64 s[2:3], |v98|, s94
	v_cmp_le_f32_e64 s[4:5], |v171|, s94
	s_cbranch_vccnz .LBB0_198
	v_pk_add_f32 v[102:103], v[98:99], s[10:11] op_sel_hi:[0,1]
	v_and_b32_e32 v100, 0x7fffffff, v98
	v_and_b32_e32 v101, 0x7fffffff, v171
	v_pk_fma_f32 v[100:101], v[100:101], v[96:97], v[64:65] op_sel_hi:[1,0,1]
	v_and_b32_e32 v105, 0x7fffffff, v103
	v_and_b32_e32 v104, 0x7fffffff, v102
	v_cndmask_b32_e64 v99, v143, v100, s[2:3]
	v_pk_fma_f32 v[104:105], v[104:105], v[96:97], v[80:81] op_sel_hi:[1,0,1]
	v_cmp_le_f32_e64 vcc, |v103|, s94
	v_pk_add_f32 v[106:107], v[98:99], s[54:55] op_sel_hi:[0,1]
	v_cndmask_b32_e64 v101, v143, v101, s[4:5]
	v_cndmask_b32_e32 v100, v143, v105, vcc
	v_cmp_le_f32_e64 vcc, |v102|, s94
	v_pk_add_f32 v[102:103], v[98:99], s[52:53] op_sel_hi:[0,1]
	v_and_b32_e32 v105, 0x7fffffff, v103
	v_cndmask_b32_e32 v97, v143, v104, vcc
	v_and_b32_e32 v104, 0x7fffffff, v102
	v_pk_fma_f32 v[146:147], v[104:105], v[96:97], v[66:67] op_sel_hi:[1,0,1]
	v_cmp_le_f32_e64 vcc, |v103|, s94
	v_max3_f32 v148, v99, s95, v101
	v_max3_f32 v149, v97, s95, v100
	v_cndmask_b32_e32 v104, v143, v147, vcc
	v_cmp_le_f32_e64 vcc, |v102|, s94
	v_and_b32_e32 v147, 0x7fffffff, v107
	s_mov_b64 s[86:87], 0
	v_cndmask_b32_e32 v102, v143, v146, vcc
	v_and_b32_e32 v146, 0x7fffffff, v106
	v_pk_fma_f32 v[146:147], v[146:147], v[96:97], v[82:83] op_sel_hi:[1,0,1]
	v_cmp_le_f32_e64 vcc, |v107|, s94
	v_max3_f32 v152, v148, v102, v104
	s_nop 0
	v_cndmask_b32_e32 v105, v143, v147, vcc
	v_cmp_le_f32_e64 vcc, |v106|, s94
	v_pk_add_f32 v[106:107], v[98:99], s[56:57] op_sel_hi:[0,1]
	v_and_b32_e32 v147, 0x7fffffff, v107
	v_cndmask_b32_e32 v103, v143, v146, vcc
	v_and_b32_e32 v146, 0x7fffffff, v106
	v_pk_fma_f32 v[150:151], v[146:147], v[96:97], v[68:69] op_sel_hi:[1,0,1]
	v_cmp_le_f32_e64 vcc, |v107|, s94
	v_max3_f32 v153, v149, v103, v105
	v_pk_add_f32 v[148:149], v[98:99], s[58:59] op_sel_hi:[0,1]
	v_cndmask_b32_e32 v146, v143, v151, vcc
	v_cmp_le_f32_e64 vcc, |v106|, s94
	v_and_b32_e32 v151, 0x7fffffff, v149
	s_nop 0
	v_cndmask_b32_e32 v106, v143, v150, vcc
	v_and_b32_e32 v150, 0x7fffffff, v148
	v_pk_fma_f32 v[150:151], v[150:151], v[96:97], v[84:85] op_sel_hi:[1,0,1]
	v_cmp_le_f32_e64 vcc, |v149|, s94
	v_max3_f32 v156, v152, v106, v146
	s_nop 0
	v_cndmask_b32_e32 v147, v143, v151, vcc
	v_cmp_le_f32_e64 vcc, |v148|, s94
	v_pk_add_f32 v[148:149], v[98:99], s[60:61] op_sel_hi:[0,1]
	v_and_b32_e32 v151, 0x7fffffff, v149
	v_cndmask_b32_e32 v107, v143, v150, vcc
	v_and_b32_e32 v150, 0x7fffffff, v148
	v_pk_fma_f32 v[154:155], v[150:151], v[96:97], v[70:71] op_sel_hi:[1,0,1]
	v_cmp_le_f32_e64 vcc, |v149|, s94
	v_max3_f32 v157, v153, v107, v147
	v_pk_add_f32 v[152:153], v[98:99], s[62:63] op_sel_hi:[0,1]
	v_cndmask_b32_e32 v150, v143, v155, vcc
	v_cmp_le_f32_e64 vcc, |v148|, s94
	v_and_b32_e32 v155, 0x7fffffff, v153
	s_nop 0
	v_cndmask_b32_e32 v148, v143, v154, vcc
	v_and_b32_e32 v154, 0x7fffffff, v152
	v_pk_fma_f32 v[154:155], v[154:155], v[96:97], v[86:87] op_sel_hi:[1,0,1]
	v_cmp_le_f32_e64 vcc, |v153|, s94
	v_max3_f32 v160, v156, v148, v150
	s_nop 0
	v_cndmask_b32_e32 v151, v143, v155, vcc
	v_cmp_le_f32_e64 vcc, |v152|, s94
	v_pk_add_f32 v[152:153], v[98:99], s[64:65] op_sel_hi:[0,1]
	v_and_b32_e32 v155, 0x7fffffff, v153
	v_cndmask_b32_e32 v149, v143, v154, vcc
	v_and_b32_e32 v154, 0x7fffffff, v152
	v_pk_fma_f32 v[158:159], v[154:155], v[96:97], v[72:73] op_sel_hi:[1,0,1]
	v_cmp_le_f32_e64 vcc, |v153|, s94
	v_max3_f32 v161, v157, v149, v151
	v_pk_add_f32 v[156:157], v[98:99], s[66:67] op_sel_hi:[0,1]
	v_cndmask_b32_e32 v154, v143, v159, vcc
	v_cmp_le_f32_e64 vcc, |v152|, s94
	v_and_b32_e32 v159, 0x7fffffff, v157
	s_nop 0
	v_cndmask_b32_e32 v152, v143, v158, vcc
	v_and_b32_e32 v158, 0x7fffffff, v156
	v_pk_fma_f32 v[158:159], v[158:159], v[96:97], v[88:89] op_sel_hi:[1,0,1]
	v_cmp_le_f32_e64 vcc, |v157|, s94
	v_max3_f32 v164, v160, v152, v154
	s_nop 0
	v_cndmask_b32_e32 v155, v143, v159, vcc
	v_cmp_le_f32_e64 vcc, |v156|, s94
	v_pk_add_f32 v[156:157], v[98:99], s[72:73] op_sel_hi:[0,1]
	v_and_b32_e32 v159, 0x7fffffff, v157
	v_cndmask_b32_e32 v153, v143, v158, vcc
	v_and_b32_e32 v158, 0x7fffffff, v156
	v_pk_fma_f32 v[162:163], v[158:159], v[96:97], v[74:75] op_sel_hi:[1,0,1]
	v_cmp_le_f32_e64 vcc, |v157|, s94
	v_max3_f32 v165, v161, v153, v155
	v_pk_add_f32 v[160:161], v[98:99], s[74:75] op_sel_hi:[0,1]
	v_cndmask_b32_e32 v158, v143, v163, vcc
	v_cmp_le_f32_e64 vcc, |v156|, s94
	v_and_b32_e32 v163, 0x7fffffff, v161
	s_nop 0
	v_cndmask_b32_e32 v156, v143, v162, vcc
	v_and_b32_e32 v162, 0x7fffffff, v160
	v_pk_fma_f32 v[162:163], v[162:163], v[96:97], v[90:91] op_sel_hi:[1,0,1]
	v_cmp_le_f32_e64 vcc, |v161|, s94
	v_max3_f32 v168, v164, v156, v158
	s_nop 0
	v_cndmask_b32_e32 v159, v143, v163, vcc
	v_cmp_le_f32_e64 vcc, |v160|, s94
	v_pk_add_f32 v[160:161], v[98:99], s[76:77] op_sel_hi:[0,1]
	v_and_b32_e32 v163, 0x7fffffff, v161
	v_cndmask_b32_e32 v157, v143, v162, vcc
	v_and_b32_e32 v162, 0x7fffffff, v160
	v_max3_f32 v169, v165, v157, v159
	v_pk_add_f32 v[164:165], v[98:99], s[78:79] op_sel_hi:[0,1]
	v_pk_fma_f32 v[162:163], v[162:163], v[96:97], v[76:77] op_sel_hi:[1,0,1]
	v_cmp_le_f32_e64 vcc, |v161|, s94
	v_and_b32_e32 v167, 0x7fffffff, v165
	v_and_b32_e32 v166, 0x7fffffff, v164
	v_cndmask_b32_e32 v163, v143, v163, vcc
	v_cmp_le_f32_e64 vcc, |v160|, s94
	v_pk_fma_f32 v[166:167], v[166:167], v[96:97], v[92:93] op_sel_hi:[1,0,1]
	s_nop 0
	v_cndmask_b32_e32 v161, v143, v162, vcc
	v_cmp_le_f32_e64 vcc, |v165|, s94
	v_max3_f32 v174, v168, v161, v163
	s_nop 0
	v_cndmask_b32_e32 v162, v143, v167, vcc
	v_cmp_le_f32_e64 vcc, |v164|, s94
	v_pk_add_f32 v[164:165], v[98:99], s[80:81] op_sel_hi:[0,1]
	v_and_b32_e32 v167, 0x7fffffff, v165
	v_cndmask_b32_e32 v160, v143, v166, vcc
	v_and_b32_e32 v166, 0x7fffffff, v164
	v_max3_f32 v175, v169, v160, v162
	v_pk_add_f32 v[168:169], v[98:99], s[82:83] op_sel_hi:[0,1]
	v_pk_fma_f32 v[166:167], v[166:167], v[96:97], v[78:79] op_sel_hi:[1,0,1]
	v_cmp_le_f32_e64 vcc, |v165|, s94
	v_and_b32_e32 v173, 0x7fffffff, v169
	v_and_b32_e32 v172, 0x7fffffff, v168
	v_cndmask_b32_e32 v167, v143, v167, vcc
	v_cmp_le_f32_e64 vcc, |v164|, s94
	v_pk_fma_f32 v[172:173], v[172:173], v[96:97], v[94:95] op_sel_hi:[1,0,1]
	s_nop 0
	v_cndmask_b32_e32 v165, v143, v166, vcc
	v_cmp_le_f32_e64 vcc, |v169|, s94
	s_nop 1
	v_cndmask_b32_e32 v166, v143, v173, vcc
	v_cmp_le_f32_e64 vcc, |v168|, s94
	v_max3_f32 v168, v174, v165, v167
	s_nop 0
	v_cndmask_b32_e32 v164, v143, v172, vcc
	v_max3_f32 v169, v175, v164, v166

.LBB0_211:
	s_cmp_eq_u32 s100, 1
	s_cbranch_scc1 .Ldil_ret12
	s_cmp_lt_i32 s35, 4
	s_cbranch_scc1 .LBB0_220
	v_mbcnt_lo_u32_b32 v0, -1, 0
	v_mbcnt_hi_u32_b32 v0, -1, v0
	s_waitcnt vmcnt(0) lgkmcnt(0)
	s_waitcnt lgkmcnt(0)
	v_add_u32_e32 v0, s84, v0
	v_cmp_gt_u32_e32 vcc, 64, v0
	s_barrier
	s_and_saveexec_b64 s[0:1], vcc
	s_cbranch_execz .LBB0_219
	buffer_wbl2 sc1
	s_waitcnt vmcnt(0)
	s_waitcnt vmcnt(0)
	v_cmp_eq_u32_e32 vcc, 0, v0
	s_and_saveexec_b64 s[2:3], vcc
	s_cbranch_execz .LBB0_218
	s_mov_b64 s[6:7], exec
	v_mbcnt_lo_u32_b32 v0, s6, 0
	v_mbcnt_hi_u32_b32 v0, s7, v0
	v_cmp_eq_u32_e32 vcc, 0, v0
	s_and_saveexec_b64 s[4:5], vcc
	s_cbranch_execz .LBB0_216
	s_bcnt1_i32_b64 s6, s[6:7]
	v_mov_b32_e32 v0, 0
	v_mov_b32_e32 v1, s6
	global_atomic_add v0, v1, s[14:15]

.LBB0_254:
	s_cmp_gt_i32 s34, 4
	s_cselect_b64 s[0:1], -1, 0
	s_cmp_lt_i32 s35, 5
	s_cselect_b64 s[2:3], -1, 0
	s_or_b64 s[0:1], s[0:1], s[2:3]
	s_and_b64 vcc, exec, s[0:1]
	s_cbranch_vccnz .LBB0_298
	s_mov_b32 s99, 0
.Lmla_body:
	s_cmpk_gt_i32 s12, 0x5ff
	s_waitcnt vmcnt(0)
	v_mbcnt_lo_u32_b32 v0, -1, 0
	v_mbcnt_hi_u32_b32 v0, -1, v0
	s_cbranch_scc1 .LBB0_289
	v_add_u32_e32 v5, s84, v0
	v_ashrrev_i32_e32 v6, 3, v5
	v_and_b32_e32 v12, 0x1fffff0, v6
	v_lshlrev_b32_e32 v13, 1, v6
	v_lshlrev_b32_e32 v7, 3, v5
	v_and_or_b32 v12, v13, 8, v12
	s_add_u32 s16, s70, 0x17a0000
	v_and_b32_e32 v152, 56, v7
	v_and_b32_e32 v8, 24, v7
	v_lshrrev_b32_e32 v12, 2, v12
	v_bfe_u32 v7, v7, 5, 1
	s_addc_u32 s17, s71, 0
	v_lshrrev_b32_e32 v13, 1, v6
	v_or_b32_e32 v7, v12, v7
	v_and_b32_e32 v12, 3, v6
	s_add_u32 s18, s70, 0x77a0000
	v_and_or_b32 v12, v13, 4, v12
	v_lshlrev_b32_e32 v13, 1, v152
	s_addc_u32 s19, s71, 0
	v_and_b32_e32 v14, 48, v13
	s_add_u32 s20, s70, 0xbfa0000
	v_lshl_or_b32 v12, v12, 6, v14
	v_lshlrev_b32_e32 v14, 4, v6
	s_addc_u32 s21, s71, 0
	v_lshl_or_b32 v12, v7, 9, v12
	v_lshlrev_b32_e32 v7, 8, v6
	v_and_b32_e32 v14, 0xf0, v14
	s_add_u32 s22, s70, 0x1eba0000
	v_bfe_u32 v11, v5, 2, 6
	v_bitop3_b32 v193, v13, v7, v14 bitop3:0xde
	v_mov_b32_e32 v14, 0x80
	v_lshlrev_b32_e32 v15, 2, v5
	s_addc_u32 s23, s71, 0
	v_ashrrev_i32_e32 v1, 6, v5
	v_and_b32_e32 v2, 0x3fffffc0, v5
	s_add_i32 s0, 0, 0x12000
	v_lshlrev_b32_e32 v7, 8, v11
	v_lshl_or_b32 v14, v8, 1, v14
	v_and_b32_e32 v15, 0xf0, v15
	v_and_b32_e32 v3, 63, v0
	v_and_b32_e32 v9, 31, v0
	v_lshl_add_u32 v153, v2, 2, s0
	v_lshlrev_b32_e32 v2, 5, v1
	v_bitop3_b32 v194, v14, v7, v15 bitop3:0xde
	v_lshlrev_b32_e32 v14, 4, v0
	v_or_b32_e32 v192, v2, v9
	s_movk_i32 s0, 0x600
	v_lshlrev_b32_e32 v7, 3, v3
	v_and_b32_e32 v15, 0xc0, v14
	v_lshlrev_b32_e32 v16, 1, v0
	v_mad_i64_i32 v[148:149], s[0:1], v192, s0, 0
	v_and_or_b32 v15, v7, 24, v15
	v_and_b32_e32 v16, 32, v16
	v_and_b32_e32 v7, 0x100, v7
	s_cmp_lg_u32 0, -1
	v_bfe_u32 v10, v0, 5, 1
	v_or3_b32 v7, v15, v16, v7
	s_cselect_b32 s0, 0, 0
	v_add_u32_e32 v195, s0, v7
	v_ashrrev_i32_e32 v7, 31, v6
	v_lshlrev_b32_e32 v197, 4, v10
	v_lshlrev_b64 v[154:155], 11, v[6:7]
	v_add_u32_e32 v196, 0, v12
	v_lshlrev_b32_e32 v7, 8, v9
	v_and_b32_e32 v12, 0xf0, v14
	v_or_b32_e32 v14, 32, v197
	v_bitop3_b32 v199, v14, v7, v12 bitop3:0xde
	v_or_b32_e32 v14, 64, v197
	v_bitop3_b32 v200, v14, v7, v12 bitop3:0xde
	v_or_b32_e32 v14, 0x60, v197
	v_bitop3_b32 v201, v14, v7, v12 bitop3:0xde
	v_or_b32_e32 v14, 0x80, v197
	s_mov_b64 s[0:1], 0x20000
	v_bitop3_b32 v202, v14, v7, v12 bitop3:0xde
	v_or_b32_e32 v14, 0xa0, v197
	s_add_i32 s2, 0, 0x12800
	v_lshl_add_u64 v[156:157], v[154:155], 0, s[0:1]
	v_bitop3_b32 v198, v197, v7, v12 bitop3:0xde
	v_bitop3_b32 v203, v14, v7, v12 bitop3:0xde
	v_cmp_gt_u32_e64 s[0:1], 32, v3
	v_lshl_add_u32 v1, v1, 12, s2
	v_lshlrev_b32_e32 v3, 9, v10
	v_lshlrev_b32_e32 v7, 1, v9
	v_add3_u32 v205, v1, v3, v7
	v_ashrrev_i32_e32 v3, 31, v2
	v_lshlrev_b64 v[160:161], 11, v[2:3]
	v_bfe_u32 v3, v0, 3, 3
	v_add_u32_e32 v7, v1, v13
	v_or_b32_e32 v1, 8, v3
	v_lshlrev_b32_e32 v4, 3, v10
	v_lshlrev_b32_e32 v13, 7, v1
	v_lshlrev_b32_e32 v10, 10, v1
	v_or_b32_e32 v1, 16, v3
	v_mov_b32_e32 v151, 0
	v_lshlrev_b32_e32 v15, 7, v1
	v_lshlrev_b32_e32 v12, 10, v1
	v_or_b32_e32 v1, 24, v3
	v_and_b32_e32 v150, 32, v0
	v_lshl_add_u32 v204, v9, 2, v153
	v_lshlrev_b32_e32 v9, 7, v3
	v_lshlrev_b32_e32 v2, 10, v3
	v_lshlrev_b32_e32 v3, 7, v1
	v_lshlrev_b32_e32 v14, 10, v1
	v_lshl_add_u64 v[0:1], s[70:71], 0, v[150:151]
	s_mov_b64 s[6:7], 0x16a0000
	v_lshl_add_u64 v[162:163], v[0:1], 0, s[6:7]
	s_mov_b64 s[6:7], 0x1720000
	v_lshl_add_u64 v[164:165], v[0:1], 0, s[6:7]
	v_and_b32_e32 v0, 3, v5
	v_lshlrev_b32_e32 v0, 4, v0
	v_lshlrev_b32_e32 v6, 5, v11
	s_mov_b64 s[4:5], 0x40000
	v_lshl_or_b32 v166, v11, 6, v0
	v_lshlrev_b32_e32 v0, 4, v5
	s_movk_i32 s2, 0x70
	s_mov_b32 s3, 0
	v_lshl_add_u64 v[158:159], v[154:155], 0, s[4:5]
	v_mov_b32_e32 v167, v151
	v_and_or_b32 v168, v0, s2, v154
	v_mov_b32_e32 v169, v155
	s_movk_i32 s24, 0x2000
	s_mov_b32 s25, 0x41000000
	s_mov_b64 s[6:7], 0x2000
	v_add_u32_e32 v206, v7, v9
	v_lshlrev_b32_e32 v170, 1, v2
	v_add_u32_e32 v207, v7, v13
	v_lshlrev_b32_e32 v172, 1, v10
	v_add_u32_e32 v208, v7, v15
	v_lshlrev_b32_e32 v174, 1, v12
	v_add_u32_e32 v209, v7, v3
	v_lshlrev_b32_e32 v176, 1, v14
	v_lshlrev_b32_e32 v178, 1, v4
	v_lshlrev_b32_e32 v180, 1, v6
	v_lshlrev_b32_e32 v182, 1, v8
	s_mov_b32 s26, s12
	s_branch .LBB0_258

.LBB0_263:
	s_mov_b32 s29, s28
	s_mov_b32 s28, s52
	s_barrier
	s_lshl_b32 s30, s29, 14
	s_add_i32 s30, s30, 0
	v_add_u32_e32 v36, s30, v198
	ds_read_b128 v[32:35], v36 offset:24576
	ds_read_b128 v[36:39], v36 offset:32768
	v_add_u32_e32 v40, s30, v199
	v_add_u32_e32 v44, s30, v200
	v_add_u32_e32 v173, s30, v201
	s_waitcnt lgkmcnt(1)
	v_mfma_f32_32x32x16_bf16 v[96:111], v[32:35], v[116:119], v[48:63]
	ds_read_b128 v[32:35], v40 offset:24576
	ds_read_b128 v[40:43], v40 offset:32768
	v_add_u32_e32 v177, s30, v202
	v_exp_f32_e32 v64, v64
	v_exp_f32_e32 v65, v65
	v_exp_f32_e32 v66, v66
	v_exp_f32_e32 v67, v67
	v_exp_f32_e32 v68, v68
	s_waitcnt lgkmcnt(2)
	v_mfma_f32_32x32x16_bf16 v[80:95], v[36:39], v[116:119], v[48:63]
	ds_read_b128 v[36:39], v44 offset:24576
	ds_read_b128 v[44:47], v44 offset:32768
	ds_read_b128 v[224:227], v173 offset:24576
	ds_read_b128 v[228:231], v173 offset:32768
	ds_read_b128 v[232:235], v177 offset:24576
	ds_read_b128 v[236:239], v177 offset:32768
	v_exp_f32_e32 v69, v69
	v_add_u32_e32 v179, s30, v203
	s_waitcnt lgkmcnt(7)
	v_mfma_f32_32x32x16_bf16 v[96:111], v[32:35], v[112:115], v[96:111]
	ds_read_b128 v[32:35], v179 offset:24576
	ds_read_b128 v[240:243], v179 offset:32768
	s_waitcnt lgkmcnt(8)
	v_mfma_f32_32x32x16_bf16 v[80:95], v[40:43], v[112:115], v[80:95]
	v_exp_f32_e32 v40, v70
	v_exp_f32_e32 v41, v71
	v_exp_f32_e32 v42, v72
	v_exp_f32_e32 v43, v73
	v_exp_f32_e32 v70, v74
	v_exp_f32_e32 v71, v75
	v_exp_f32_e32 v72, v76
	s_waitcnt lgkmcnt(7)
	v_mfma_f32_32x32x16_bf16 v[96:111], v[36:39], v[124:127], v[96:111]
	v_add_f32_e32 v36, 0, v215
	v_add_f32_e32 v36, v219, v36
	v_add_f32_e32 v36, v216, v36
	v_add_f32_e32 v36, v220, v36
	v_add_f32_e32 v36, v217, v36
	v_add_f32_e32 v36, v221, v36
	v_add_f32_e32 v36, v218, v36
	s_waitcnt lgkmcnt(6)
	v_mfma_f32_32x32x16_bf16 v[80:95], v[44:47], v[124:127], v[80:95]
	v_add_f32_e32 v36, v222, v36
	v_add_f32_e32 v36, v188, v36
	v_add_f32_e32 v36, v211, v36
	v_add_f32_e32 v36, v189, v36
	v_add_f32_e32 v36, v212, v36
	v_add_f32_e32 v36, v190, v36
	v_add_f32_e32 v36, v213, v36
	s_waitcnt lgkmcnt(5)
	v_mfma_f32_32x32x16_bf16 v[96:111], v[224:227], v[120:123], v[96:111]
	v_add_f32_e32 v36, v191, v36
	v_add_f32_e32 v36, v214, v36
	v_add_f32_e32 v36, v64, v36
	v_add_f32_e32 v36, v65, v36
	v_add_f32_e32 v36, v66, v36
	v_add_f32_e32 v36, v67, v36
	v_add_f32_e32 v36, v68, v36
	s_waitcnt lgkmcnt(4)
	v_mfma_f32_32x32x16_bf16 v[80:95], v[228:231], v[120:123], v[80:95]
	v_add_f32_e32 v36, v69, v36
	v_add_f32_e32 v36, v40, v36
	v_add_f32_e32 v36, v41, v36
	v_add_f32_e32 v36, v42, v36
	v_exp_f32_e32 v73, v77
	v_add_f32_e32 v36, v43, v36
	v_exp_f32_e32 v74, v78
	s_waitcnt lgkmcnt(3)
	v_mfma_f32_32x32x16_bf16 v[96:111], v[232:235], v[132:135], v[96:111]
	v_add_f32_e32 v36, v70, v36
	v_exp_f32_e32 v75, v79
	v_add_f32_e32 v36, v71, v36
	v_add_f32_e32 v36, v72, v36
	v_add_f32_e32 v36, v73, v36
	v_add_f32_e32 v36, v74, v36
	v_add_f32_e32 v177, v75, v36
	s_waitcnt lgkmcnt(2)
	v_mfma_f32_32x32x16_bf16 v[80:95], v[236:239], v[132:135], v[80:95]
	v_mov_b32_e32 v179, v177
	v_cvt_pk_bf16_f32 v36, v215, v219
	v_cvt_pk_bf16_f32 v37, v216, v220
	v_cvt_pk_bf16_f32 v38, v217, v221
	v_cvt_pk_bf16_f32 v39, v218, v222
	v_cvt_pk_bf16_f32 v44, v64, v65
	v_cvt_pk_bf16_f32 v45, v66, v67
	s_waitcnt lgkmcnt(1)
	v_mfma_f32_32x32x16_bf16 v[96:111], v[32:35], v[128:131], v[96:111]
	v_cvt_pk_bf16_f32 v32, v188, v211
	v_cvt_pk_bf16_f32 v33, v189, v212
	v_cvt_pk_bf16_f32 v34, v190, v213
	v_cvt_pk_bf16_f32 v35, v191, v214
	v_cvt_pk_bf16_f32 v46, v68, v69
	v_cvt_pk_bf16_f32 v47, v40, v41
	v_cvt_pk_bf16_f32 v40, v42, v43
	s_waitcnt lgkmcnt(0)
	v_mfma_f32_32x32x16_bf16 v[80:95], v[240:243], v[128:131], v[80:95]
	s_lshl_b32 s31, s28, 13
	v_add_u32_e32 v173, s31, v195
	v_cvt_pk_bf16_f32 v41, v70, v71
	v_cvt_pk_bf16_f32 v42, v72, v73
	v_cvt_pk_bf16_f32 v43, v74, v75
	ds_read_b64_tr_b16 v[64:65], v173 offset:0
	ds_read_b64_tr_b16 v[66:67], v173 offset:0x400
	ds_read_b64_tr_b16 v[68:69], v173 offset:0x800
	ds_read_b64_tr_b16 v[70:71], v173 offset:0xc00
	ds_read_b64_tr_b16 v[72:73], v173 offset:0x1000
	ds_read_b64_tr_b16 v[74:75], v173 offset:0x1400
	ds_read_b64_tr_b16 v[76:77], v173 offset:0x1800
	ds_read_b64_tr_b16 v[78:79], v173 offset:0x1c00
	v_permlane32_swap_b32_e32 v177, v179
	v_permlane32_swap_b32_e32 v36, v38
	v_permlane32_swap_b32_e32 v37, v39
	v_permlane32_swap_b32_e32 v32, v34
	v_permlane32_swap_b32_e32 v33, v35
	v_permlane32_swap_b32_e32 v44, v46
	v_permlane32_swap_b32_e32 v45, v47
	v_permlane32_swap_b32_e32 v40, v42
	v_permlane32_swap_b32_e32 v41, v43
	ds_read_b64_tr_b16 v[224:225], v173 offset:0x200
	ds_read_b64_tr_b16 v[226:227], v173 offset:0x600
	ds_read_b64_tr_b16 v[228:229], v173 offset:0xa00
	ds_read_b64_tr_b16 v[230:231], v173 offset:0xe00
	ds_read_b64_tr_b16 v[232:233], v173 offset:0x1200
	ds_read_b64_tr_b16 v[234:235], v173 offset:0x1600
	ds_read_b64_tr_b16 v[236:237], v173 offset:0x1a00
	s_waitcnt lgkmcnt(7)
	s_nop 0
	v_mfma_f32_32x32x16_bf16 v[0:15], v[36:39], v[64:67], v[0:15]
	ds_read_b64_tr_b16 v[238:239], v173 offset:0x1e00
	s_lshl_b32 s30, s9, 13
	s_lshl_b32 s33, s9, 14
	v_add_u32_e32 v245, s30, v196
	s_waitcnt vmcnt(0)
	ds_write_b128 v245, v[136:139]
	v_add_u32_e32 v245, s33, v193
	s_add_i32 s98, s2, 1
	ds_write_b128 v245, v[140:143] offset:24576
	v_add_u32_e32 v245, s33, v194
	s_cmp_ge_u32 s98, s27
	v_lshl_add_u64 v[190:191], s[70:71], 0, v[186:187]
	v_lshl_add_u64 v[188:189], s[70:71], 0, v[184:185]
	ds_write_b128 v245, v[144:147] offset:24576
	s_cbranch_scc1 .LBB0_265
	v_add_co_u32_e32 v246, vcc, 0xc000000, v190
	s_nop 1
	v_addc_co_u32_e32 v247, vcc, 0, v191, vcc
	global_load_dwordx4 v[136:139], v[246:247], off offset:128
	global_load_dwordx4 v[140:143], v[246:247], off
	v_add_co_u32_e32 v246, vcc, 0x1eba3000, v188
	s_nop 1
	v_addc_co_u32_e32 v247, vcc, 0, v189, vcc
	global_load_dwordx4 v[144:147], v[246:247], off
.LBB0_265:
	v_mfma_f32_32x32x16_bf16 v[0:15], v[32:35], v[68:71], v[0:15]
	v_mfma_f32_32x32x16_bf16 v[0:15], v[44:47], v[72:75], v[0:15]
	v_mfma_f32_32x32x16_bf16 v[0:15], v[40:43], v[76:79], v[0:15]
	s_waitcnt lgkmcnt(0)
	v_mfma_f32_32x32x16_bf16 v[16:31], v[36:39], v[224:227], v[16:31]
	v_max_f32_e32 v76, v97, v97
	v_max_f32_e32 v77, v96, v96
	v_max_f32_e32 v76, v77, v76
	v_max3_f32 v76, v76, v98, v99
	v_max3_f32 v36, v76, v100, v101
	v_max3_f32 v36, v36, v102, v103
	v_max3_f32 v36, v36, v104, v105
	v_mfma_f32_32x32x16_bf16 v[16:31], v[32:35], v[228:231], v[16:31]
	v_max3_f32 v36, v36, v106, v107
	v_max3_f32 v36, v36, v108, v109
	v_max3_f32 v36, v36, v110, v111
	v_max3_f32 v36, v36, v80, v81
	v_max3_f32 v32, v36, v82, v83
	v_max3_f32 v32, v32, v84, v85
	v_max3_f32 v32, v32, v86, v87
	v_mfma_f32_32x32x16_bf16 v[16:31], v[44:47], v[232:235], v[16:31]
	v_max3_f32 v32, v32, v88, v89
	v_max3_f32 v32, v32, v90, v91
	v_max3_f32 v32, v32, v92, v93
	v_max3_f32 v32, v32, v94, v95
	v_mov_b32_e32 v33, v32
	s_nop 1
	v_permlane32_swap_b32_e32 v32, v33
	v_mfma_f32_32x32x16_bf16 v[16:31], v[40:43], v[236:239], v[16:31]
	v_max_f32_e32 v33, v33, v33
	v_max_f32_e32 v32, v32, v32
	v_max_f32_e32 v32, v32, v33
	v_cmp_ge_f32_e32 vcc, s25, v32
	s_cmp_eq_u64 vcc, exec
	s_cbranch_scc0 .LBB0_279
	v_mov_b64_e32 v[32:33], v[48:49]
	v_mov_b32_e32 v181, 1.0
	v_mov_b64_e32 v[34:35], v[50:51]
	v_mov_b64_e32 v[36:37], v[52:53]
	v_mov_b64_e32 v[38:39], v[54:55]
	v_mov_b64_e32 v[40:41], v[56:57]
	v_mov_b64_e32 v[42:43], v[58:59]
	v_mov_b64_e32 v[44:45], v[60:61]
	v_mov_b64_e32 v[46:47], v[62:63]
	v_cmp_gt_f32_e32 vcc, 1.0, v181
	s_cbranch_vccz .LBB0_270

.LBB0_270:
	v_exp_f32_e32 v218, v96
	v_exp_f32_e32 v219, v97
	v_exp_f32_e32 v220, v98
	v_exp_f32_e32 v221, v99
	v_exp_f32_e32 v222, v100
	v_exp_f32_e32 v223, v101
	v_exp_f32_e32 v224, v102
	v_exp_f32_e32 v225, v103
	v_exp_f32_e32 v226, v104
	v_exp_f32_e32 v227, v105
	v_exp_f32_e32 v228, v106
	v_exp_f32_e32 v229, v107
	v_exp_f32_e32 v230, v108
	v_exp_f32_e32 v231, v109
	v_exp_f32_e32 v232, v110
	v_exp_f32_e32 v233, v111
	s_waitcnt lgkmcnt(0)
	s_barrier
	v_add_u32_e32 v68, s33, v198
	ds_read_b128 v[64:67], v68 offset:24576
	ds_read_b128 v[210:213], v68 offset:32768
	v_add_u32_e32 v183, s33, v199
	v_exp_f32_e32 v87, v87
	v_exp_f32_e32 v88, v88
	s_waitcnt lgkmcnt(1)
	v_mfma_f32_32x32x16_bf16 v[96:111], v[64:67], v[116:119], v[32:47]
	v_exp_f32_e32 v89, v89
	v_exp_f32_e32 v90, v90
	v_exp_f32_e32 v91, v91
	v_exp_f32_e32 v234, v92
	v_exp_f32_e32 v235, v93
	v_exp_f32_e32 v236, v94
	v_exp_f32_e32 v237, v95
	s_waitcnt lgkmcnt(0)
	v_mfma_f32_32x32x16_bf16 v[64:79], v[210:213], v[116:119], v[32:47]
	ds_read_b128 v[210:213], v183 offset:24576
	ds_read_b128 v[214:217], v183 offset:32768
	v_add_u32_e32 v183, s33, v200
	v_cvt_pk_bf16_f32 v92, v218, v219
	v_cvt_pk_bf16_f32 v93, v220, v221
	v_cvt_pk_bf16_f32 v94, v222, v223
	v_cvt_pk_bf16_f32 v95, v224, v225
	s_waitcnt lgkmcnt(1)
	v_mfma_f32_32x32x16_bf16 v[96:111], v[210:213], v[112:115], v[96:111]
	v_permlane32_swap_b32_e32 v92, v94
	v_permlane32_swap_b32_e32 v93, v95
	s_waitcnt lgkmcnt(0)
	v_mfma_f32_32x32x16_bf16 v[64:79], v[214:217], v[112:115], v[64:79]
	ds_read_b128 v[210:213], v183 offset:24576
	ds_read_b128 v[214:217], v183 offset:32768
	v_add_u32_e32 v183, s33, v201
	s_waitcnt lgkmcnt(1)
	v_mfma_f32_32x32x16_bf16 v[96:111], v[210:213], v[124:127], v[96:111]
	s_waitcnt lgkmcnt(0)
	v_mfma_f32_32x32x16_bf16 v[64:79], v[214:217], v[124:127], v[64:79]
	ds_read_b128 v[210:213], v183 offset:24576
	ds_read_b128 v[214:217], v183 offset:32768
	v_add_u32_e32 v183, s33, v202
	s_waitcnt lgkmcnt(1)
	v_mfma_f32_32x32x16_bf16 v[96:111], v[210:213], v[120:123], v[96:111]
	s_waitcnt lgkmcnt(0)
	v_mfma_f32_32x32x16_bf16 v[64:79], v[214:217], v[120:123], v[64:79]
	ds_read_b128 v[210:213], v183 offset:24576
	ds_read_b128 v[214:217], v183 offset:32768
	v_add_u32_e32 v183, s33, v203
	s_waitcnt lgkmcnt(1)
	v_mfma_f32_32x32x16_bf16 v[96:111], v[210:213], v[132:135], v[96:111]
	s_waitcnt lgkmcnt(0)
	v_mfma_f32_32x32x16_bf16 v[64:79], v[214:217], v[132:135], v[64:79]
	ds_read_b128 v[210:213], v183 offset:24576
	ds_read_b128 v[214:217], v183 offset:32768
	s_waitcnt lgkmcnt(1)
	v_mfma_f32_32x32x16_bf16 v[96:111], v[210:213], v[128:131], v[96:111]
	v_exp_f32_e32 v211, v80
	v_add_f32_e32 v80, 0, v218
	v_add_f32_e32 v80, v219, v80
	v_add_f32_e32 v80, v220, v80
	v_add_f32_e32 v80, v221, v80
	v_add_f32_e32 v80, v222, v80
	v_add_f32_e32 v80, v223, v80
	v_add_f32_e32 v80, v224, v80
	v_add_f32_e32 v80, v225, v80
	v_add_f32_e32 v80, v226, v80
	v_add_f32_e32 v80, v227, v80
	v_add_f32_e32 v80, v228, v80
	v_add_f32_e32 v80, v229, v80
	v_add_f32_e32 v80, v230, v80
	v_exp_f32_e32 v212, v81
	v_add_f32_e32 v80, v231, v80
	v_exp_f32_e32 v213, v82
	v_add_f32_e32 v80, v232, v80
	s_waitcnt lgkmcnt(0)
	v_mfma_f32_32x32x16_bf16 v[64:79], v[214:217], v[128:131], v[64:79]
	v_exp_f32_e32 v214, v83
	v_add_f32_e32 v80, v233, v80
	v_exp_f32_e32 v215, v84
	v_add_f32_e32 v80, v211, v80
	v_exp_f32_e32 v216, v85
	v_add_f32_e32 v80, v212, v80
	v_exp_f32_e32 v217, v86
	v_add_f32_e32 v80, v213, v80
	v_add_f32_e32 v80, v214, v80
	v_add_f32_e32 v80, v215, v80
	v_add_f32_e32 v80, v216, v80
	v_add_f32_e32 v80, v217, v80
	v_add_f32_e32 v80, v87, v80
	v_add_f32_e32 v80, v88, v80
	v_add_f32_e32 v80, v89, v80
	v_add_f32_e32 v80, v90, v80
	v_add_f32_e32 v80, v91, v80
	v_add_f32_e32 v80, v234, v80
	v_add_f32_e32 v80, v235, v80
	v_add_f32_e32 v80, v236, v80
	v_add_f32_e32 v183, v237, v80
	v_mov_b32_e32 v210, v183
	v_cvt_pk_bf16_f32 v80, v226, v227
	v_cvt_pk_bf16_f32 v81, v228, v229
	v_cvt_pk_bf16_f32 v82, v230, v231
	v_cvt_pk_bf16_f32 v83, v232, v233
	v_cvt_pk_bf16_f32 v84, v211, v212
	v_cvt_pk_bf16_f32 v85, v213, v214
	v_cvt_pk_bf16_f32 v86, v215, v216
	v_cvt_pk_bf16_f32 v87, v217, v87
	v_cvt_pk_bf16_f32 v88, v88, v89
	v_cvt_pk_bf16_f32 v89, v90, v91
	v_cvt_pk_bf16_f32 v90, v234, v235
	v_cvt_pk_bf16_f32 v91, v236, v237
	v_lshl_add_u32 v211, s29, 13, v195
	ds_read_b64_tr_b16 v[212:213], v211 offset:0
	ds_read_b64_tr_b16 v[214:215], v211 offset:0x400
	ds_read_b64_tr_b16 v[216:217], v211 offset:0x800
	ds_read_b64_tr_b16 v[218:219], v211 offset:0xc00
	ds_read_b64_tr_b16 v[220:221], v211 offset:0x1000
	ds_read_b64_tr_b16 v[222:223], v211 offset:0x1400
	ds_read_b64_tr_b16 v[224:225], v211 offset:0x1800
	ds_read_b64_tr_b16 v[226:227], v211 offset:0x1c00
	s_nop 1
	v_permlane32_swap_b32_e32 v183, v210
	v_permlane32_swap_b32_e32 v80, v82
	v_permlane32_swap_b32_e32 v81, v83
	v_permlane32_swap_b32_e32 v84, v86
	v_permlane32_swap_b32_e32 v85, v87
	v_permlane32_swap_b32_e32 v88, v90
	v_permlane32_swap_b32_e32 v89, v91
	ds_read_b64_tr_b16 v[228:229], v211 offset:0x200
	ds_read_b64_tr_b16 v[230:231], v211 offset:0x600
	ds_read_b64_tr_b16 v[232:233], v211 offset:0xa00
	ds_read_b64_tr_b16 v[234:235], v211 offset:0xe00
	ds_read_b64_tr_b16 v[236:237], v211 offset:0x1200
	ds_read_b64_tr_b16 v[238:239], v211 offset:0x1600
	ds_read_b64_tr_b16 v[240:241], v211 offset:0x1a00
	s_waitcnt lgkmcnt(7)
	s_nop 0
	v_mfma_f32_32x32x16_bf16 v[0:15], v[92:95], v[212:215], v[0:15]
	ds_read_b64_tr_b16 v[242:243], v211 offset:0x1e00
	v_add_u32_e32 v245, s31, v196
	s_lshl_b32 s31, s28, 14
	s_add_i32 s31, s31, 0
	s_add_i32 s2, s2, 2
	s_cmp_ge_u32 s2, s27
	s_waitcnt vmcnt(2)
	ds_write_b128 v245, v[136:139]
	v_add_u32_e32 v245, s31, v193
	s_cselect_b64 s[52:53], -1, 0
	s_waitcnt vmcnt(1)
	ds_write_b128 v245, v[140:143] offset:24576
	v_add_u32_e32 v245, s31, v194
	s_and_b64 vcc, exec, s[52:53]
	s_waitcnt vmcnt(0)
	ds_write_b128 v245, v[144:147] offset:24576
	s_cbranch_vccnz .LBB0_272
	v_add_co_u32_e32 v140, vcc, 0xc020000, v190
	s_nop 1
	v_addc_co_u32_e32 v141, vcc, 0, v191, vcc
	v_add_co_u32_e32 v144, vcc, 0x1eba4000, v188
	global_load_dwordx4 v[136:139], v[140:141], off offset:128
	s_nop 0
	global_load_dwordx4 v[140:143], v[140:141], off
	v_addc_co_u32_e32 v145, vcc, 0, v189, vcc
	global_load_dwordx4 v[144:147], v[144:145], off
.LBB0_272:
	v_mfma_f32_32x32x16_bf16 v[0:15], v[80:83], v[216:219], v[0:15]
	v_mfma_f32_32x32x16_bf16 v[0:15], v[84:87], v[220:223], v[0:15]
	v_mfma_f32_32x32x16_bf16 v[0:15], v[88:91], v[224:227], v[0:15]
	s_waitcnt lgkmcnt(0)
	v_mfma_f32_32x32x16_bf16 v[16:31], v[92:95], v[228:231], v[16:31]
	v_max_f32_e32 v211, v97, v97
	v_max_f32_e32 v220, v96, v96
	v_max_f32_e32 v211, v220, v211
	v_max3_f32 v211, v211, v98, v99
	v_max3_f32 v211, v211, v100, v101
	v_max3_f32 v92, v211, v102, v103
	v_max3_f32 v92, v92, v104, v105
	v_mfma_f32_32x32x16_bf16 v[16:31], v[80:83], v[232:235], v[16:31]
	v_max3_f32 v92, v92, v106, v107
	v_max3_f32 v92, v92, v108, v109
	v_max3_f32 v92, v92, v110, v111
	v_max3_f32 v92, v92, v64, v65
	v_max3_f32 v92, v92, v66, v67
	v_max3_f32 v80, v92, v68, v69
	v_max3_f32 v80, v80, v70, v71
	v_mfma_f32_32x32x16_bf16 v[16:31], v[84:87], v[236:239], v[16:31]
	v_max3_f32 v80, v80, v72, v73
	v_max3_f32 v80, v80, v74, v75
	v_max3_f32 v80, v80, v76, v77
	v_max3_f32 v80, v80, v78, v79
	v_mov_b32_e32 v81, v80
	s_nop 1
	v_permlane32_swap_b32_e32 v80, v81
	v_mfma_f32_32x32x16_bf16 v[16:31], v[88:91], v[240:243], v[16:31]
	v_max_f32_e32 v81, v81, v81
	v_max_f32_e32 v80, v80, v80
	v_max_f32_e32 v81, v80, v81
	v_cmp_ge_f32_e32 vcc, s25, v81
	s_cmp_eq_u64 vcc, exec
	v_mov_b32_e32 v80, 1.0
	s_cbranch_scc0 .LBB0_280
	v_cmp_gt_f32_e32 vcc, 1.0, v80
	s_cbranch_vccz .LBB0_277

.LBB0_289:
	s_cmp_eq_u32 s99, 1
	s_cbranch_scc1 .Lmla_ret14
	s_cmp_lt_i32 s35, 6
	s_cbranch_scc1 .LBB0_298
	v_mbcnt_lo_u32_b32 v0, -1, 0
	v_mbcnt_hi_u32_b32 v0, -1, v0
	s_waitcnt vmcnt(0) lgkmcnt(0)
	s_waitcnt lgkmcnt(0)
	v_add_u32_e32 v0, s84, v0
	v_cmp_gt_u32_e32 vcc, 64, v0
	s_barrier
	s_and_saveexec_b64 s[0:1], vcc
	s_cbranch_execz .LBB0_297
	buffer_wbl2 sc1
	s_waitcnt vmcnt(0)
	s_waitcnt vmcnt(0)
	v_cmp_eq_u32_e32 vcc, 0, v0
	s_and_saveexec_b64 s[2:3], vcc
	s_cbranch_execz .LBB0_296
	s_mov_b64 s[6:7], exec
	v_mbcnt_lo_u32_b32 v0, s6, 0
	v_mbcnt_hi_u32_b32 v0, s7, v0
	v_cmp_eq_u32_e32 vcc, 0, v0
	s_and_saveexec_b64 s[4:5], vcc
	s_cbranch_execz .LBB0_294
	s_bcnt1_i32_b64 s6, s[6:7]
	v_mov_b32_e32 v0, 0
	v_mov_b32_e32 v1, s6
	global_atomic_add v0, v1, s[14:15]

.LBB0_554:
	s_or_b64 exec, exec, s[20:21]
	s_mov_b32 s100, 1
	s_branch .Ldil_body
.Ldil_ret12:
.LBB0_590:
	s_cmp_lt_i32 s35, 14
	s_cbranch_scc1 .LBB0_599
	v_mbcnt_lo_u32_b32 v0, -1, 0
	v_mbcnt_hi_u32_b32 v0, -1, v0
	s_waitcnt vmcnt(0) lgkmcnt(0)
	s_waitcnt lgkmcnt(0)
	v_add_u32_e32 v0, s84, v0
	v_cmp_gt_u32_e32 vcc, 64, v0
	s_barrier
	s_and_saveexec_b64 s[0:1], vcc
	s_cbranch_execz .LBB0_598
	buffer_wbl2 sc1
	s_waitcnt vmcnt(0)
	s_waitcnt vmcnt(0)
	v_cmp_eq_u32_e32 vcc, 0, v0
	s_and_saveexec_b64 s[2:3], vcc
	s_cbranch_execz .LBB0_597
	s_mov_b64 s[6:7], exec
	v_mbcnt_lo_u32_b32 v0, s6, 0
	v_mbcnt_hi_u32_b32 v0, s7, v0
	v_cmp_eq_u32_e32 vcc, 0, v0
	s_and_saveexec_b64 s[4:5], vcc
	s_cbranch_execz .LBB0_595
	s_bcnt1_i32_b64 s6, s[6:7]
	v_mov_b32_e32 v0, 0
	v_mov_b32_e32 v1, s6
	global_atomic_add v0, v1, s[14:15]

.LBB0_633:
	s_cmp_gt_i32 s34, 14
	s_cselect_b64 s[0:1], -1, 0
	s_cmp_lt_i32 s35, 15
	s_cselect_b64 s[2:3], -1, 0
	s_or_b64 s[0:1], s[0:1], s[2:3]
	s_and_b64 vcc, exec, s[0:1]
	s_cbranch_vccnz .LBB0_677
	s_mov_b32 s99, 1
	s_branch .Lmla_body
.Lmla_ret14:
.LBB0_668:
	s_cmp_lt_i32 s35, 16
	s_cbranch_scc1 .LBB0_677
	v_mbcnt_lo_u32_b32 v0, -1, 0
	v_mbcnt_hi_u32_b32 v0, -1, v0
	s_waitcnt vmcnt(0) lgkmcnt(0)
	s_waitcnt lgkmcnt(0)
	v_add_u32_e32 v0, s84, v0
	v_cmp_gt_u32_e32 vcc, 64, v0
	s_barrier
	s_and_saveexec_b64 s[0:1], vcc
	s_cbranch_execz .LBB0_676
	buffer_wbl2 sc1
	s_waitcnt vmcnt(0)
	s_waitcnt vmcnt(0)
	v_cmp_eq_u32_e32 vcc, 0, v0
	s_and_saveexec_b64 s[2:3], vcc
	s_cbranch_execz .LBB0_675
	s_mov_b64 s[6:7], exec
	v_mbcnt_lo_u32_b32 v0, s6, 0
	v_mbcnt_hi_u32_b32 v0, s7, v0
	v_cmp_eq_u32_e32 vcc, 0, v0
	s_and_saveexec_b64 s[4:5], vcc
	s_cbranch_execz .LBB0_673
	s_bcnt1_i32_b64 s6, s[6:7]
	v_mov_b32_e32 v0, 0
	v_mov_b32_e32 v1, s6
	global_atomic_add v0, v1, s[14:15]

	.amdhsa_kernel _Z14fwd_megakernel6Params
		.amdhsa_group_segment_fixed_size 0
		.amdhsa_private_segment_fixed_size 0
		.amdhsa_kernarg_size 408
		.amdhsa_user_sgpr_count 2
		.amdhsa_user_sgpr_dispatch_ptr 0
		.amdhsa_user_sgpr_queue_ptr 0
		.amdhsa_user_sgpr_kernarg_segment_ptr 1
		.amdhsa_user_sgpr_dispatch_id 0
		.amdhsa_user_sgpr_kernarg_preload_length 0
		.amdhsa_user_sgpr_kernarg_preload_offset 0
		.amdhsa_user_sgpr_private_segment_size 0
		.amdhsa_uses_dynamic_stack 0
		.amdhsa_enable_private_segment 0
		.amdhsa_system_sgpr_workgroup_id_x 1
		.amdhsa_system_sgpr_workgroup_id_y 0
		.amdhsa_system_sgpr_workgroup_id_z 0
		.amdhsa_system_sgpr_workgroup_info 0
		.amdhsa_system_vgpr_workitem_id 2
		.amdhsa_next_free_vgpr 256
		.amdhsa_next_free_sgpr 102
		.amdhsa_accum_offset 256
		.amdhsa_reserve_vcc 1
		.amdhsa_float_round_mode_32 0
		.amdhsa_float_round_mode_16_64 0
		.amdhsa_float_denorm_mode_32 3
		.amdhsa_float_denorm_mode_16_64 3
		.amdhsa_dx10_clamp 1
		.amdhsa_ieee_mode 1
		.amdhsa_fp16_overflow 0
		.amdhsa_tg_split 0
		.amdhsa_exception_fp_ieee_invalid_op 0
		.amdhsa_exception_fp_denorm_src 0
		.amdhsa_exception_fp_ieee_div_zero 0
		.amdhsa_exception_fp_ieee_overflow 0
		.amdhsa_exception_fp_ieee_underflow 0
		.amdhsa_exception_fp_ieee_inexact 0
		.amdhsa_exception_int_div_zero 0
	.end_amdhsa_kernel

amdhsa.kernels:
  - .agpr_count:     0
    .args:
      - .offset:         0
        .size:           152
        .value_kind:     by_value
      - .offset:         152
        .size:           4
        .value_kind:     hidden_block_count_x
      - .offset:         156
        .size:           4
        .value_kind:     hidden_block_count_y
      - .offset:         160
        .size:           4
        .value_kind:     hidden_block_count_z
      - .offset:         164
        .size:           2
        .value_kind:     hidden_group_size_x
      - .offset:         166
        .size:           2
        .value_kind:     hidden_group_size_y
      - .offset:         168
        .size:           2
        .value_kind:     hidden_group_size_z
      - .offset:         170
        .size:           2
        .value_kind:     hidden_remainder_x
      - .offset:         172
        .size:           2
        .value_kind:     hidden_remainder_y
      - .offset:         174
        .size:           2
        .value_kind:     hidden_remainder_z
      - .offset:         192
        .size:           8
        .value_kind:     hidden_global_offset_x
      - .offset:         200
        .size:           8
        .value_kind:     hidden_global_offset_y
      - .offset:         208
        .size:           8
        .value_kind:     hidden_global_offset_z
      - .offset:         216
        .size:           2
        .value_kind:     hidden_grid_dims
      - .offset:         240
        .size:           8
        .value_kind:     hidden_multigrid_sync_arg
      - .offset:         272
        .size:           4
        .value_kind:     hidden_dynamic_lds_size
    .group_segment_fixed_size: 0
    .kernarg_segment_align: 8
    .kernarg_segment_size: 408
    .language:       OpenCL C
    .language_version:
      - 2
      - 0
    .max_flat_workgroup_size: 512
    .name:           _Z14fwd_megakernel6Params
    .private_segment_fixed_size: 0
    .sgpr_count:     108
    .sgpr_spill_count: 16
    .symbol:         _Z14fwd_megakernel6Params.kd
    .uniform_work_group_size: 1
    .uses_dynamic_stack: false
    .vgpr_count:     256
    .vgpr_spill_count: 0
    .wavefront_size: 64
